# conv_out epilogue: all 16 gate tiles requested up front, compute and store as they arrive
# speedup vs baseline: 1.0069x; 1.0069x over previous
.LBB0_682:
	s_andn2_b64 vcc, exec, s[4:5]
	s_mov_b64 s[4:5], -1
	v_lshl_add_u32 v158, s36, 8, v148
	v_lshl_or_b32 v159, s53, 8, v150
	v_lshlrev_b32_e32 v158, 11, v158
	v_lshl_add_u32 v144, v159, 1, v158
	v_add_u32_e32 v145, 0x8000, v144
	v_add_u32_e32 v146, 0x10000, v144
	v_add_u32_e32 v147, 0x18000, v144
	v_add_u32_e32 v154, 0x40000, v144
	v_add_u32_e32 v155, 0x48000, v144
	v_add_u32_e32 v156, 0x50000, v144
	v_add_u32_e32 v157, 0x58000, v144
	global_load_dwordx4 v[178:181], v144, s[12:13]
	global_load_dwordx4 v[182:185], v144, s[12:13] offset:256
	global_load_dwordx4 v[186:189], v145, s[12:13]
	global_load_dwordx4 v[190:193], v145, s[12:13] offset:256
	global_load_dwordx4 v[194:197], v146, s[12:13]
	global_load_dwordx4 v[198:201], v146, s[12:13] offset:256
	global_load_dwordx4 v[202:205], v147, s[12:13]
	global_load_dwordx4 v[206:209], v147, s[12:13] offset:256
	global_load_dwordx4 v[210:213], v154, s[12:13]
	global_load_dwordx4 v[214:217], v154, s[12:13] offset:256
	global_load_dwordx4 v[218:221], v155, s[12:13]
	global_load_dwordx4 v[222:225], v155, s[12:13] offset:256
	global_load_dwordx4 v[226:229], v156, s[12:13]
	global_load_dwordx4 v[230:233], v156, s[12:13] offset:256
	global_load_dwordx4 v[234:237], v157, s[12:13]
	global_load_dwordx4 v[238:241], v157, s[12:13] offset:256
	s_waitcnt vmcnt(15)
	v_lshlrev_b32_e32 v160, 16, v178
	v_lshlrev_b32_e32 v161, 16, v179
	v_lshlrev_b32_e32 v162, 16, v180
	v_lshlrev_b32_e32 v163, 16, v181
	v_and_b32_e32 v178, 0xffff0000, v178
	v_and_b32_e32 v179, 0xffff0000, v179
	v_and_b32_e32 v180, 0xffff0000, v180
	v_and_b32_e32 v181, 0xffff0000, v181
	v_mul_f32_e32 v160, 0xbfb8aa3b, v160
	v_mul_f32_e32 v178, 0xbfb8aa3b, v178
	v_mul_f32_e32 v161, 0xbfb8aa3b, v161
	v_mul_f32_e32 v179, 0xbfb8aa3b, v179
	v_mul_f32_e32 v162, 0xbfb8aa3b, v162
	v_mul_f32_e32 v180, 0xbfb8aa3b, v180
	v_mul_f32_e32 v163, 0xbfb8aa3b, v163
	v_mul_f32_e32 v181, 0xbfb8aa3b, v181
	v_exp_f32_e32 v160, v160
	v_exp_f32_e32 v178, v178
	v_exp_f32_e32 v161, v161
	v_exp_f32_e32 v179, v179
	v_exp_f32_e32 v162, v162
	v_exp_f32_e32 v180, v180
	v_exp_f32_e32 v163, v163
	v_exp_f32_e32 v181, v181
	v_add_f32_e32 v160, 1.0, v160
	v_add_f32_e32 v178, 1.0, v178
	v_add_f32_e32 v161, 1.0, v161
	v_add_f32_e32 v179, 1.0, v179
	v_add_f32_e32 v162, 1.0, v162
	v_add_f32_e32 v180, 1.0, v180
	v_add_f32_e32 v163, 1.0, v163
	v_add_f32_e32 v181, 1.0, v181
	v_rcp_f32_e32 v160, v160
	v_rcp_f32_e32 v178, v178
	v_rcp_f32_e32 v161, v161
	v_rcp_f32_e32 v179, v179
	v_rcp_f32_e32 v162, v162
	v_rcp_f32_e32 v180, v180
	v_rcp_f32_e32 v163, v163
	v_rcp_f32_e32 v181, v181
	v_mul_f32_e32 v124, v124, v160
	v_mul_f32_e32 v125, v125, v178
	v_mul_f32_e32 v126, v126, v161
	v_mul_f32_e32 v127, v127, v179
	v_mul_f32_e32 v120, v120, v162
	v_mul_f32_e32 v121, v121, v180
	v_mul_f32_e32 v122, v122, v163
	v_mul_f32_e32 v123, v123, v181
	v_cvt_pk_bf16_f32 v124, v124, v125
	v_cvt_pk_bf16_f32 v125, v126, v127
	v_cvt_pk_bf16_f32 v126, v120, v121
	v_cvt_pk_bf16_f32 v127, v122, v123
	global_store_dwordx4 v144, v[124:127], s[12:13]
	s_waitcnt vmcnt(15)
	v_lshlrev_b32_e32 v160, 16, v182
	v_lshlrev_b32_e32 v161, 16, v183
	v_lshlrev_b32_e32 v162, 16, v184
	v_lshlrev_b32_e32 v163, 16, v185
	v_and_b32_e32 v182, 0xffff0000, v182
	v_and_b32_e32 v183, 0xffff0000, v183
	v_and_b32_e32 v184, 0xffff0000, v184
	v_and_b32_e32 v185, 0xffff0000, v185
	v_mul_f32_e32 v160, 0xbfb8aa3b, v160
	v_mul_f32_e32 v182, 0xbfb8aa3b, v182
	v_mul_f32_e32 v161, 0xbfb8aa3b, v161
	v_mul_f32_e32 v183, 0xbfb8aa3b, v183
	v_mul_f32_e32 v162, 0xbfb8aa3b, v162
	v_mul_f32_e32 v184, 0xbfb8aa3b, v184
	v_mul_f32_e32 v163, 0xbfb8aa3b, v163
	v_mul_f32_e32 v185, 0xbfb8aa3b, v185
	v_exp_f32_e32 v160, v160
	v_exp_f32_e32 v182, v182
	v_exp_f32_e32 v161, v161
	v_exp_f32_e32 v183, v183
	v_exp_f32_e32 v162, v162
	v_exp_f32_e32 v184, v184
	v_exp_f32_e32 v163, v163
	v_exp_f32_e32 v185, v185
	v_add_f32_e32 v160, 1.0, v160
	v_add_f32_e32 v182, 1.0, v182
	v_add_f32_e32 v161, 1.0, v161
	v_add_f32_e32 v183, 1.0, v183
	v_add_f32_e32 v162, 1.0, v162
	v_add_f32_e32 v184, 1.0, v184
	v_add_f32_e32 v163, 1.0, v163
	v_add_f32_e32 v185, 1.0, v185
	v_rcp_f32_e32 v160, v160
	v_rcp_f32_e32 v182, v182
	v_rcp_f32_e32 v161, v161
	v_rcp_f32_e32 v183, v183
	v_rcp_f32_e32 v162, v162
	v_rcp_f32_e32 v184, v184
	v_rcp_f32_e32 v163, v163
	v_rcp_f32_e32 v185, v185
	v_mul_f32_e32 v116, v116, v160
	v_mul_f32_e32 v117, v117, v182
	v_mul_f32_e32 v118, v118, v161
	v_mul_f32_e32 v119, v119, v183
	v_mul_f32_e32 v112, v112, v162
	v_mul_f32_e32 v113, v113, v184
	v_mul_f32_e32 v114, v114, v163
	v_mul_f32_e32 v115, v115, v185
	v_cvt_pk_bf16_f32 v116, v116, v117
	v_cvt_pk_bf16_f32 v117, v118, v119
	v_cvt_pk_bf16_f32 v118, v112, v113
	v_cvt_pk_bf16_f32 v119, v114, v115
	global_store_dwordx4 v144, v[116:119], s[12:13] offset:256
	s_waitcnt vmcnt(15)
	v_lshlrev_b32_e32 v160, 16, v186
	v_lshlrev_b32_e32 v161, 16, v187
	v_lshlrev_b32_e32 v162, 16, v188
	v_lshlrev_b32_e32 v163, 16, v189
	v_and_b32_e32 v186, 0xffff0000, v186
	v_and_b32_e32 v187, 0xffff0000, v187
	v_and_b32_e32 v188, 0xffff0000, v188
	v_and_b32_e32 v189, 0xffff0000, v189
	v_mul_f32_e32 v160, 0xbfb8aa3b, v160
	v_mul_f32_e32 v186, 0xbfb8aa3b, v186
	v_mul_f32_e32 v161, 0xbfb8aa3b, v161
	v_mul_f32_e32 v187, 0xbfb8aa3b, v187
	v_mul_f32_e32 v162, 0xbfb8aa3b, v162
	v_mul_f32_e32 v188, 0xbfb8aa3b, v188
	v_mul_f32_e32 v163, 0xbfb8aa3b, v163
	v_mul_f32_e32 v189, 0xbfb8aa3b, v189
	v_exp_f32_e32 v160, v160
	v_exp_f32_e32 v186, v186
	v_exp_f32_e32 v161, v161
	v_exp_f32_e32 v187, v187
	v_exp_f32_e32 v162, v162
	v_exp_f32_e32 v188, v188
	v_exp_f32_e32 v163, v163
	v_exp_f32_e32 v189, v189
	v_add_f32_e32 v160, 1.0, v160
	v_add_f32_e32 v186, 1.0, v186
	v_add_f32_e32 v161, 1.0, v161
	v_add_f32_e32 v187, 1.0, v187
	v_add_f32_e32 v162, 1.0, v162
	v_add_f32_e32 v188, 1.0, v188
	v_add_f32_e32 v163, 1.0, v163
	v_add_f32_e32 v189, 1.0, v189
	v_rcp_f32_e32 v160, v160
	v_rcp_f32_e32 v186, v186
	v_rcp_f32_e32 v161, v161
	v_rcp_f32_e32 v187, v187
	v_rcp_f32_e32 v162, v162
	v_rcp_f32_e32 v188, v188
	v_rcp_f32_e32 v163, v163
	v_rcp_f32_e32 v189, v189
	v_mul_f32_e32 v108, v108, v160
	v_mul_f32_e32 v109, v109, v186
	v_mul_f32_e32 v110, v110, v161
	v_mul_f32_e32 v111, v111, v187
	v_mul_f32_e32 v104, v104, v162
	v_mul_f32_e32 v105, v105, v188
	v_mul_f32_e32 v106, v106, v163
	v_mul_f32_e32 v107, v107, v189
	v_cvt_pk_bf16_f32 v108, v108, v109
	v_cvt_pk_bf16_f32 v109, v110, v111
	v_cvt_pk_bf16_f32 v110, v104, v105
	v_cvt_pk_bf16_f32 v111, v106, v107
	global_store_dwordx4 v145, v[108:111], s[12:13]
	s_waitcnt vmcnt(15)
	v_lshlrev_b32_e32 v160, 16, v190
	v_lshlrev_b32_e32 v161, 16, v191
	v_lshlrev_b32_e32 v162, 16, v192
	v_lshlrev_b32_e32 v163, 16, v193
	v_and_b32_e32 v190, 0xffff0000, v190
	v_and_b32_e32 v191, 0xffff0000, v191
	v_and_b32_e32 v192, 0xffff0000, v192
	v_and_b32_e32 v193, 0xffff0000, v193
	v_mul_f32_e32 v160, 0xbfb8aa3b, v160
	v_mul_f32_e32 v190, 0xbfb8aa3b, v190
	v_mul_f32_e32 v161, 0xbfb8aa3b, v161
	v_mul_f32_e32 v191, 0xbfb8aa3b, v191
	v_mul_f32_e32 v162, 0xbfb8aa3b, v162
	v_mul_f32_e32 v192, 0xbfb8aa3b, v192
	v_mul_f32_e32 v163, 0xbfb8aa3b, v163
	v_mul_f32_e32 v193, 0xbfb8aa3b, v193
	v_exp_f32_e32 v160, v160
	v_exp_f32_e32 v190, v190
	v_exp_f32_e32 v161, v161
	v_exp_f32_e32 v191, v191
	v_exp_f32_e32 v162, v162
	v_exp_f32_e32 v192, v192
	v_exp_f32_e32 v163, v163
	v_exp_f32_e32 v193, v193
	v_add_f32_e32 v160, 1.0, v160
	v_add_f32_e32 v190, 1.0, v190
	v_add_f32_e32 v161, 1.0, v161
	v_add_f32_e32 v191, 1.0, v191
	v_add_f32_e32 v162, 1.0, v162
	v_add_f32_e32 v192, 1.0, v192
	v_add_f32_e32 v163, 1.0, v163
	v_add_f32_e32 v193, 1.0, v193
	v_rcp_f32_e32 v160, v160
	v_rcp_f32_e32 v190, v190
	v_rcp_f32_e32 v161, v161
	v_rcp_f32_e32 v191, v191
	v_rcp_f32_e32 v162, v162
	v_rcp_f32_e32 v192, v192
	v_rcp_f32_e32 v163, v163
	v_rcp_f32_e32 v193, v193
	v_mul_f32_e32 v100, v100, v160
	v_mul_f32_e32 v101, v101, v190
	v_mul_f32_e32 v102, v102, v161
	v_mul_f32_e32 v103, v103, v191
	v_mul_f32_e32 v96, v96, v162
	v_mul_f32_e32 v97, v97, v192
	v_mul_f32_e32 v98, v98, v163
	v_mul_f32_e32 v99, v99, v193
	v_cvt_pk_bf16_f32 v100, v100, v101
	v_cvt_pk_bf16_f32 v101, v102, v103
	v_cvt_pk_bf16_f32 v102, v96, v97
	v_cvt_pk_bf16_f32 v103, v98, v99
	global_store_dwordx4 v145, v[100:103], s[12:13] offset:256
	s_waitcnt vmcnt(15)
	v_lshlrev_b32_e32 v160, 16, v194
	v_lshlrev_b32_e32 v161, 16, v195
	v_lshlrev_b32_e32 v162, 16, v196
	v_lshlrev_b32_e32 v163, 16, v197
	v_and_b32_e32 v194, 0xffff0000, v194
	v_and_b32_e32 v195, 0xffff0000, v195
	v_and_b32_e32 v196, 0xffff0000, v196
	v_and_b32_e32 v197, 0xffff0000, v197
	v_mul_f32_e32 v160, 0xbfb8aa3b, v160
	v_mul_f32_e32 v194, 0xbfb8aa3b, v194
	v_mul_f32_e32 v161, 0xbfb8aa3b, v161
	v_mul_f32_e32 v195, 0xbfb8aa3b, v195
	v_mul_f32_e32 v162, 0xbfb8aa3b, v162
	v_mul_f32_e32 v196, 0xbfb8aa3b, v196
	v_mul_f32_e32 v163, 0xbfb8aa3b, v163
	v_mul_f32_e32 v197, 0xbfb8aa3b, v197
	v_exp_f32_e32 v160, v160
	v_exp_f32_e32 v194, v194
	v_exp_f32_e32 v161, v161
	v_exp_f32_e32 v195, v195
	v_exp_f32_e32 v162, v162
	v_exp_f32_e32 v196, v196
	v_exp_f32_e32 v163, v163
	v_exp_f32_e32 v197, v197
	v_add_f32_e32 v160, 1.0, v160
	v_add_f32_e32 v194, 1.0, v194
	v_add_f32_e32 v161, 1.0, v161
	v_add_f32_e32 v195, 1.0, v195
	v_add_f32_e32 v162, 1.0, v162
	v_add_f32_e32 v196, 1.0, v196
	v_add_f32_e32 v163, 1.0, v163
	v_add_f32_e32 v197, 1.0, v197
	v_rcp_f32_e32 v160, v160
	v_rcp_f32_e32 v194, v194
	v_rcp_f32_e32 v161, v161
	v_rcp_f32_e32 v195, v195
	v_rcp_f32_e32 v162, v162
	v_rcp_f32_e32 v196, v196
	v_rcp_f32_e32 v163, v163
	v_rcp_f32_e32 v197, v197
	v_mul_f32_e32 v92, v92, v160
	v_mul_f32_e32 v93, v93, v194
	v_mul_f32_e32 v94, v94, v161
	v_mul_f32_e32 v95, v95, v195
	v_mul_f32_e32 v88, v88, v162
	v_mul_f32_e32 v89, v89, v196
	v_mul_f32_e32 v90, v90, v163
	v_mul_f32_e32 v91, v91, v197
	v_cvt_pk_bf16_f32 v92, v92, v93
	v_cvt_pk_bf16_f32 v93, v94, v95
	v_cvt_pk_bf16_f32 v94, v88, v89
	v_cvt_pk_bf16_f32 v95, v90, v91
	global_store_dwordx4 v146, v[92:95], s[12:13]
	s_waitcnt vmcnt(15)
	v_lshlrev_b32_e32 v160, 16, v198
	v_lshlrev_b32_e32 v161, 16, v199
	v_lshlrev_b32_e32 v162, 16, v200
	v_lshlrev_b32_e32 v163, 16, v201
	v_and_b32_e32 v198, 0xffff0000, v198
	v_and_b32_e32 v199, 0xffff0000, v199
	v_and_b32_e32 v200, 0xffff0000, v200
	v_and_b32_e32 v201, 0xffff0000, v201
	v_mul_f32_e32 v160, 0xbfb8aa3b, v160
	v_mul_f32_e32 v198, 0xbfb8aa3b, v198
	v_mul_f32_e32 v161, 0xbfb8aa3b, v161
	v_mul_f32_e32 v199, 0xbfb8aa3b, v199
	v_mul_f32_e32 v162, 0xbfb8aa3b, v162
	v_mul_f32_e32 v200, 0xbfb8aa3b, v200
	v_mul_f32_e32 v163, 0xbfb8aa3b, v163
	v_mul_f32_e32 v201, 0xbfb8aa3b, v201
	v_exp_f32_e32 v160, v160
	v_exp_f32_e32 v198, v198
	v_exp_f32_e32 v161, v161
	v_exp_f32_e32 v199, v199
	v_exp_f32_e32 v162, v162
	v_exp_f32_e32 v200, v200
	v_exp_f32_e32 v163, v163
	v_exp_f32_e32 v201, v201
	v_add_f32_e32 v160, 1.0, v160
	v_add_f32_e32 v198, 1.0, v198
	v_add_f32_e32 v161, 1.0, v161
	v_add_f32_e32 v199, 1.0, v199
	v_add_f32_e32 v162, 1.0, v162
	v_add_f32_e32 v200, 1.0, v200
	v_add_f32_e32 v163, 1.0, v163
	v_add_f32_e32 v201, 1.0, v201
	v_rcp_f32_e32 v160, v160
	v_rcp_f32_e32 v198, v198
	v_rcp_f32_e32 v161, v161
	v_rcp_f32_e32 v199, v199
	v_rcp_f32_e32 v162, v162
	v_rcp_f32_e32 v200, v200
	v_rcp_f32_e32 v163, v163
	v_rcp_f32_e32 v201, v201
	v_mul_f32_e32 v84, v84, v160
	v_mul_f32_e32 v85, v85, v198
	v_mul_f32_e32 v86, v86, v161
	v_mul_f32_e32 v87, v87, v199
	v_mul_f32_e32 v80, v80, v162
	v_mul_f32_e32 v81, v81, v200
	v_mul_f32_e32 v82, v82, v163
	v_mul_f32_e32 v83, v83, v201
	v_cvt_pk_bf16_f32 v84, v84, v85
	v_cvt_pk_bf16_f32 v85, v86, v87
	v_cvt_pk_bf16_f32 v86, v80, v81
	v_cvt_pk_bf16_f32 v87, v82, v83
	global_store_dwordx4 v146, v[84:87], s[12:13] offset:256
	s_waitcnt vmcnt(15)
	v_lshlrev_b32_e32 v160, 16, v202
	v_lshlrev_b32_e32 v161, 16, v203
	v_lshlrev_b32_e32 v162, 16, v204
	v_lshlrev_b32_e32 v163, 16, v205
	v_and_b32_e32 v202, 0xffff0000, v202
	v_and_b32_e32 v203, 0xffff0000, v203
	v_and_b32_e32 v204, 0xffff0000, v204
	v_and_b32_e32 v205, 0xffff0000, v205
	v_mul_f32_e32 v160, 0xbfb8aa3b, v160
	v_mul_f32_e32 v202, 0xbfb8aa3b, v202
	v_mul_f32_e32 v161, 0xbfb8aa3b, v161
	v_mul_f32_e32 v203, 0xbfb8aa3b, v203
	v_mul_f32_e32 v162, 0xbfb8aa3b, v162
	v_mul_f32_e32 v204, 0xbfb8aa3b, v204
	v_mul_f32_e32 v163, 0xbfb8aa3b, v163
	v_mul_f32_e32 v205, 0xbfb8aa3b, v205
	v_exp_f32_e32 v160, v160
	v_exp_f32_e32 v202, v202
	v_exp_f32_e32 v161, v161
	v_exp_f32_e32 v203, v203
	v_exp_f32_e32 v162, v162
	v_exp_f32_e32 v204, v204
	v_exp_f32_e32 v163, v163
	v_exp_f32_e32 v205, v205
	v_add_f32_e32 v160, 1.0, v160
	v_add_f32_e32 v202, 1.0, v202
	v_add_f32_e32 v161, 1.0, v161
	v_add_f32_e32 v203, 1.0, v203
	v_add_f32_e32 v162, 1.0, v162
	v_add_f32_e32 v204, 1.0, v204
	v_add_f32_e32 v163, 1.0, v163
	v_add_f32_e32 v205, 1.0, v205
	v_rcp_f32_e32 v160, v160
	v_rcp_f32_e32 v202, v202
	v_rcp_f32_e32 v161, v161
	v_rcp_f32_e32 v203, v203
	v_rcp_f32_e32 v162, v162
	v_rcp_f32_e32 v204, v204
	v_rcp_f32_e32 v163, v163
	v_rcp_f32_e32 v205, v205
	v_mul_f32_e32 v76, v76, v160
	v_mul_f32_e32 v77, v77, v202
	v_mul_f32_e32 v78, v78, v161
	v_mul_f32_e32 v79, v79, v203
	v_mul_f32_e32 v72, v72, v162
	v_mul_f32_e32 v73, v73, v204
	v_mul_f32_e32 v74, v74, v163
	v_mul_f32_e32 v75, v75, v205
	v_cvt_pk_bf16_f32 v76, v76, v77
	v_cvt_pk_bf16_f32 v77, v78, v79
	v_cvt_pk_bf16_f32 v78, v72, v73
	v_cvt_pk_bf16_f32 v79, v74, v75
	global_store_dwordx4 v147, v[76:79], s[12:13]
	s_waitcnt vmcnt(15)
	v_lshlrev_b32_e32 v160, 16, v206
	v_lshlrev_b32_e32 v161, 16, v207
	v_lshlrev_b32_e32 v162, 16, v208
	v_lshlrev_b32_e32 v163, 16, v209
	v_and_b32_e32 v206, 0xffff0000, v206
	v_and_b32_e32 v207, 0xffff0000, v207
	v_and_b32_e32 v208, 0xffff0000, v208
	v_and_b32_e32 v209, 0xffff0000, v209
	v_mul_f32_e32 v160, 0xbfb8aa3b, v160
	v_mul_f32_e32 v206, 0xbfb8aa3b, v206
	v_mul_f32_e32 v161, 0xbfb8aa3b, v161
	v_mul_f32_e32 v207, 0xbfb8aa3b, v207
	v_mul_f32_e32 v162, 0xbfb8aa3b, v162
	v_mul_f32_e32 v208, 0xbfb8aa3b, v208
	v_mul_f32_e32 v163, 0xbfb8aa3b, v163
	v_mul_f32_e32 v209, 0xbfb8aa3b, v209
	v_exp_f32_e32 v160, v160
	v_exp_f32_e32 v206, v206
	v_exp_f32_e32 v161, v161
	v_exp_f32_e32 v207, v207
	v_exp_f32_e32 v162, v162
	v_exp_f32_e32 v208, v208
	v_exp_f32_e32 v163, v163
	v_exp_f32_e32 v209, v209
	v_add_f32_e32 v160, 1.0, v160
	v_add_f32_e32 v206, 1.0, v206
	v_add_f32_e32 v161, 1.0, v161
	v_add_f32_e32 v207, 1.0, v207
	v_add_f32_e32 v162, 1.0, v162
	v_add_f32_e32 v208, 1.0, v208
	v_add_f32_e32 v163, 1.0, v163
	v_add_f32_e32 v209, 1.0, v209
	v_rcp_f32_e32 v160, v160
	v_rcp_f32_e32 v206, v206
	v_rcp_f32_e32 v161, v161
	v_rcp_f32_e32 v207, v207
	v_rcp_f32_e32 v162, v162
	v_rcp_f32_e32 v208, v208
	v_rcp_f32_e32 v163, v163
	v_rcp_f32_e32 v209, v209
	v_mul_f32_e32 v68, v68, v160
	v_mul_f32_e32 v69, v69, v206
	v_mul_f32_e32 v70, v70, v161
	v_mul_f32_e32 v71, v71, v207
	v_mul_f32_e32 v64, v64, v162
	v_mul_f32_e32 v65, v65, v208
	v_mul_f32_e32 v66, v66, v163
	v_mul_f32_e32 v67, v67, v209
	v_cvt_pk_bf16_f32 v68, v68, v69
	v_cvt_pk_bf16_f32 v69, v70, v71
	v_cvt_pk_bf16_f32 v70, v64, v65
	v_cvt_pk_bf16_f32 v71, v66, v67
	global_store_dwordx4 v147, v[68:71], s[12:13] offset:256
	s_waitcnt vmcnt(15)
	v_lshlrev_b32_e32 v160, 16, v210
	v_lshlrev_b32_e32 v161, 16, v211
	v_lshlrev_b32_e32 v162, 16, v212
	v_lshlrev_b32_e32 v163, 16, v213
	v_and_b32_e32 v210, 0xffff0000, v210
	v_and_b32_e32 v211, 0xffff0000, v211
	v_and_b32_e32 v212, 0xffff0000, v212
	v_and_b32_e32 v213, 0xffff0000, v213
	v_mul_f32_e32 v160, 0xbfb8aa3b, v160
	v_mul_f32_e32 v210, 0xbfb8aa3b, v210
	v_mul_f32_e32 v161, 0xbfb8aa3b, v161
	v_mul_f32_e32 v211, 0xbfb8aa3b, v211
	v_mul_f32_e32 v162, 0xbfb8aa3b, v162
	v_mul_f32_e32 v212, 0xbfb8aa3b, v212
	v_mul_f32_e32 v163, 0xbfb8aa3b, v163
	v_mul_f32_e32 v213, 0xbfb8aa3b, v213
	v_exp_f32_e32 v160, v160
	v_exp_f32_e32 v210, v210
	v_exp_f32_e32 v161, v161
	v_exp_f32_e32 v211, v211
	v_exp_f32_e32 v162, v162
	v_exp_f32_e32 v212, v212
	v_exp_f32_e32 v163, v163
	v_exp_f32_e32 v213, v213
	v_add_f32_e32 v160, 1.0, v160
	v_add_f32_e32 v210, 1.0, v210
	v_add_f32_e32 v161, 1.0, v161
	v_add_f32_e32 v211, 1.0, v211
	v_add_f32_e32 v162, 1.0, v162
	v_add_f32_e32 v212, 1.0, v212
	v_add_f32_e32 v163, 1.0, v163
	v_add_f32_e32 v213, 1.0, v213
	v_rcp_f32_e32 v160, v160
	v_rcp_f32_e32 v210, v210
	v_rcp_f32_e32 v161, v161
	v_rcp_f32_e32 v211, v211
	v_rcp_f32_e32 v162, v162
	v_rcp_f32_e32 v212, v212
	v_rcp_f32_e32 v163, v163
	v_rcp_f32_e32 v213, v213
	v_mul_f32_e32 v60, v60, v160
	v_mul_f32_e32 v61, v61, v210
	v_mul_f32_e32 v62, v62, v161
	v_mul_f32_e32 v63, v63, v211
	v_mul_f32_e32 v56, v56, v162
	v_mul_f32_e32 v57, v57, v212
	v_mul_f32_e32 v58, v58, v163
	v_mul_f32_e32 v59, v59, v213
	v_cvt_pk_bf16_f32 v60, v60, v61
	v_cvt_pk_bf16_f32 v61, v62, v63
	v_cvt_pk_bf16_f32 v62, v56, v57
	v_cvt_pk_bf16_f32 v63, v58, v59
	global_store_dwordx4 v154, v[60:63], s[12:13]
	s_waitcnt vmcnt(15)
	v_lshlrev_b32_e32 v160, 16, v214
	v_lshlrev_b32_e32 v161, 16, v215
	v_lshlrev_b32_e32 v162, 16, v216
	v_lshlrev_b32_e32 v163, 16, v217
	v_and_b32_e32 v214, 0xffff0000, v214
	v_and_b32_e32 v215, 0xffff0000, v215
	v_and_b32_e32 v216, 0xffff0000, v216
	v_and_b32_e32 v217, 0xffff0000, v217
	v_mul_f32_e32 v160, 0xbfb8aa3b, v160
	v_mul_f32_e32 v214, 0xbfb8aa3b, v214
	v_mul_f32_e32 v161, 0xbfb8aa3b, v161
	v_mul_f32_e32 v215, 0xbfb8aa3b, v215
	v_mul_f32_e32 v162, 0xbfb8aa3b, v162
	v_mul_f32_e32 v216, 0xbfb8aa3b, v216
	v_mul_f32_e32 v163, 0xbfb8aa3b, v163
	v_mul_f32_e32 v217, 0xbfb8aa3b, v217
	v_exp_f32_e32 v160, v160
	v_exp_f32_e32 v214, v214
	v_exp_f32_e32 v161, v161
	v_exp_f32_e32 v215, v215
	v_exp_f32_e32 v162, v162
	v_exp_f32_e32 v216, v216
	v_exp_f32_e32 v163, v163
	v_exp_f32_e32 v217, v217
	v_add_f32_e32 v160, 1.0, v160
	v_add_f32_e32 v214, 1.0, v214
	v_add_f32_e32 v161, 1.0, v161
	v_add_f32_e32 v215, 1.0, v215
	v_add_f32_e32 v162, 1.0, v162
	v_add_f32_e32 v216, 1.0, v216
	v_add_f32_e32 v163, 1.0, v163
	v_add_f32_e32 v217, 1.0, v217
	v_rcp_f32_e32 v160, v160
	v_rcp_f32_e32 v214, v214
	v_rcp_f32_e32 v161, v161
	v_rcp_f32_e32 v215, v215
	v_rcp_f32_e32 v162, v162
	v_rcp_f32_e32 v216, v216
	v_rcp_f32_e32 v163, v163
	v_rcp_f32_e32 v217, v217
	v_mul_f32_e32 v52, v52, v160
	v_mul_f32_e32 v53, v53, v214
	v_mul_f32_e32 v54, v54, v161
	v_mul_f32_e32 v55, v55, v215
	v_mul_f32_e32 v48, v48, v162
	v_mul_f32_e32 v49, v49, v216
	v_mul_f32_e32 v50, v50, v163
	v_mul_f32_e32 v51, v51, v217
	v_cvt_pk_bf16_f32 v52, v52, v53
	v_cvt_pk_bf16_f32 v53, v54, v55
	v_cvt_pk_bf16_f32 v54, v48, v49
	v_cvt_pk_bf16_f32 v55, v50, v51
	global_store_dwordx4 v154, v[52:55], s[12:13] offset:256
	s_waitcnt vmcnt(15)
	v_lshlrev_b32_e32 v160, 16, v218
	v_lshlrev_b32_e32 v161, 16, v219
	v_lshlrev_b32_e32 v162, 16, v220
	v_lshlrev_b32_e32 v163, 16, v221
	v_and_b32_e32 v218, 0xffff0000, v218
	v_and_b32_e32 v219, 0xffff0000, v219
	v_and_b32_e32 v220, 0xffff0000, v220
	v_and_b32_e32 v221, 0xffff0000, v221
	v_mul_f32_e32 v160, 0xbfb8aa3b, v160
	v_mul_f32_e32 v218, 0xbfb8aa3b, v218
	v_mul_f32_e32 v161, 0xbfb8aa3b, v161
	v_mul_f32_e32 v219, 0xbfb8aa3b, v219
	v_mul_f32_e32 v162, 0xbfb8aa3b, v162
	v_mul_f32_e32 v220, 0xbfb8aa3b, v220
	v_mul_f32_e32 v163, 0xbfb8aa3b, v163
	v_mul_f32_e32 v221, 0xbfb8aa3b, v221
	v_exp_f32_e32 v160, v160
	v_exp_f32_e32 v218, v218
	v_exp_f32_e32 v161, v161
	v_exp_f32_e32 v219, v219
	v_exp_f32_e32 v162, v162
	v_exp_f32_e32 v220, v220
	v_exp_f32_e32 v163, v163
	v_exp_f32_e32 v221, v221
	v_add_f32_e32 v160, 1.0, v160
	v_add_f32_e32 v218, 1.0, v218
	v_add_f32_e32 v161, 1.0, v161
	v_add_f32_e32 v219, 1.0, v219
	v_add_f32_e32 v162, 1.0, v162
	v_add_f32_e32 v220, 1.0, v220
	v_add_f32_e32 v163, 1.0, v163
	v_add_f32_e32 v221, 1.0, v221
	v_rcp_f32_e32 v160, v160
	v_rcp_f32_e32 v218, v218
	v_rcp_f32_e32 v161, v161
	v_rcp_f32_e32 v219, v219
	v_rcp_f32_e32 v162, v162
	v_rcp_f32_e32 v220, v220
	v_rcp_f32_e32 v163, v163
	v_rcp_f32_e32 v221, v221
	v_mul_f32_e32 v44, v44, v160
	v_mul_f32_e32 v45, v45, v218
	v_mul_f32_e32 v46, v46, v161
	v_mul_f32_e32 v47, v47, v219
	v_mul_f32_e32 v40, v40, v162
	v_mul_f32_e32 v41, v41, v220
	v_mul_f32_e32 v42, v42, v163
	v_mul_f32_e32 v43, v43, v221
	v_cvt_pk_bf16_f32 v44, v44, v45
	v_cvt_pk_bf16_f32 v45, v46, v47
	v_cvt_pk_bf16_f32 v46, v40, v41
	v_cvt_pk_bf16_f32 v47, v42, v43
	global_store_dwordx4 v155, v[44:47], s[12:13]
	s_waitcnt vmcnt(15)
	v_lshlrev_b32_e32 v160, 16, v222
	v_lshlrev_b32_e32 v161, 16, v223
	v_lshlrev_b32_e32 v162, 16, v224
	v_lshlrev_b32_e32 v163, 16, v225
	v_and_b32_e32 v222, 0xffff0000, v222
	v_and_b32_e32 v223, 0xffff0000, v223
	v_and_b32_e32 v224, 0xffff0000, v224
	v_and_b32_e32 v225, 0xffff0000, v225
	v_mul_f32_e32 v160, 0xbfb8aa3b, v160
	v_mul_f32_e32 v222, 0xbfb8aa3b, v222
	v_mul_f32_e32 v161, 0xbfb8aa3b, v161
	v_mul_f32_e32 v223, 0xbfb8aa3b, v223
	v_mul_f32_e32 v162, 0xbfb8aa3b, v162
	v_mul_f32_e32 v224, 0xbfb8aa3b, v224
	v_mul_f32_e32 v163, 0xbfb8aa3b, v163
	v_mul_f32_e32 v225, 0xbfb8aa3b, v225
	v_exp_f32_e32 v160, v160
	v_exp_f32_e32 v222, v222
	v_exp_f32_e32 v161, v161
	v_exp_f32_e32 v223, v223
	v_exp_f32_e32 v162, v162
	v_exp_f32_e32 v224, v224
	v_exp_f32_e32 v163, v163
	v_exp_f32_e32 v225, v225
	v_add_f32_e32 v160, 1.0, v160
	v_add_f32_e32 v222, 1.0, v222
	v_add_f32_e32 v161, 1.0, v161
	v_add_f32_e32 v223, 1.0, v223
	v_add_f32_e32 v162, 1.0, v162
	v_add_f32_e32 v224, 1.0, v224
	v_add_f32_e32 v163, 1.0, v163
	v_add_f32_e32 v225, 1.0, v225
	v_rcp_f32_e32 v160, v160
	v_rcp_f32_e32 v222, v222
	v_rcp_f32_e32 v161, v161
	v_rcp_f32_e32 v223, v223
	v_rcp_f32_e32 v162, v162
	v_rcp_f32_e32 v224, v224
	v_rcp_f32_e32 v163, v163
	v_rcp_f32_e32 v225, v225
	v_mul_f32_e32 v36, v36, v160
	v_mul_f32_e32 v37, v37, v222
	v_mul_f32_e32 v38, v38, v161
	v_mul_f32_e32 v39, v39, v223
	v_mul_f32_e32 v32, v32, v162
	v_mul_f32_e32 v33, v33, v224
	v_mul_f32_e32 v34, v34, v163
	v_mul_f32_e32 v35, v35, v225
	v_cvt_pk_bf16_f32 v36, v36, v37
	v_cvt_pk_bf16_f32 v37, v38, v39
	v_cvt_pk_bf16_f32 v38, v32, v33
	v_cvt_pk_bf16_f32 v39, v34, v35
	global_store_dwordx4 v155, v[36:39], s[12:13] offset:256
	s_waitcnt vmcnt(15)
	v_lshlrev_b32_e32 v160, 16, v226
	v_lshlrev_b32_e32 v161, 16, v227
	v_lshlrev_b32_e32 v162, 16, v228
	v_lshlrev_b32_e32 v163, 16, v229
	v_and_b32_e32 v226, 0xffff0000, v226
	v_and_b32_e32 v227, 0xffff0000, v227
	v_and_b32_e32 v228, 0xffff0000, v228
	v_and_b32_e32 v229, 0xffff0000, v229
	v_mul_f32_e32 v160, 0xbfb8aa3b, v160
	v_mul_f32_e32 v226, 0xbfb8aa3b, v226
	v_mul_f32_e32 v161, 0xbfb8aa3b, v161
	v_mul_f32_e32 v227, 0xbfb8aa3b, v227
	v_mul_f32_e32 v162, 0xbfb8aa3b, v162
	v_mul_f32_e32 v228, 0xbfb8aa3b, v228
	v_mul_f32_e32 v163, 0xbfb8aa3b, v163
	v_mul_f32_e32 v229, 0xbfb8aa3b, v229
	v_exp_f32_e32 v160, v160
	v_exp_f32_e32 v226, v226
	v_exp_f32_e32 v161, v161
	v_exp_f32_e32 v227, v227
	v_exp_f32_e32 v162, v162
	v_exp_f32_e32 v228, v228
	v_exp_f32_e32 v163, v163
	v_exp_f32_e32 v229, v229
	v_add_f32_e32 v160, 1.0, v160
	v_add_f32_e32 v226, 1.0, v226
	v_add_f32_e32 v161, 1.0, v161
	v_add_f32_e32 v227, 1.0, v227
	v_add_f32_e32 v162, 1.0, v162
	v_add_f32_e32 v228, 1.0, v228
	v_add_f32_e32 v163, 1.0, v163
	v_add_f32_e32 v229, 1.0, v229
	v_rcp_f32_e32 v160, v160
	v_rcp_f32_e32 v226, v226
	v_rcp_f32_e32 v161, v161
	v_rcp_f32_e32 v227, v227
	v_rcp_f32_e32 v162, v162
	v_rcp_f32_e32 v228, v228
	v_rcp_f32_e32 v163, v163
	v_rcp_f32_e32 v229, v229
	v_mul_f32_e32 v28, v28, v160
	v_mul_f32_e32 v29, v29, v226
	v_mul_f32_e32 v30, v30, v161
	v_mul_f32_e32 v31, v31, v227
	v_mul_f32_e32 v24, v24, v162
	v_mul_f32_e32 v25, v25, v228
	v_mul_f32_e32 v26, v26, v163
	v_mul_f32_e32 v27, v27, v229
	v_cvt_pk_bf16_f32 v28, v28, v29
	v_cvt_pk_bf16_f32 v29, v30, v31
	v_cvt_pk_bf16_f32 v30, v24, v25
	v_cvt_pk_bf16_f32 v31, v26, v27
	global_store_dwordx4 v156, v[28:31], s[12:13]
	s_waitcnt vmcnt(15)
	v_lshlrev_b32_e32 v160, 16, v230
	v_lshlrev_b32_e32 v161, 16, v231
	v_lshlrev_b32_e32 v162, 16, v232
	v_lshlrev_b32_e32 v163, 16, v233
	v_and_b32_e32 v230, 0xffff0000, v230
	v_and_b32_e32 v231, 0xffff0000, v231
	v_and_b32_e32 v232, 0xffff0000, v232
	v_and_b32_e32 v233, 0xffff0000, v233
	v_mul_f32_e32 v160, 0xbfb8aa3b, v160
	v_mul_f32_e32 v230, 0xbfb8aa3b, v230
	v_mul_f32_e32 v161, 0xbfb8aa3b, v161
	v_mul_f32_e32 v231, 0xbfb8aa3b, v231
	v_mul_f32_e32 v162, 0xbfb8aa3b, v162
	v_mul_f32_e32 v232, 0xbfb8aa3b, v232
	v_mul_f32_e32 v163, 0xbfb8aa3b, v163
	v_mul_f32_e32 v233, 0xbfb8aa3b, v233
	v_exp_f32_e32 v160, v160
	v_exp_f32_e32 v230, v230
	v_exp_f32_e32 v161, v161
	v_exp_f32_e32 v231, v231
	v_exp_f32_e32 v162, v162
	v_exp_f32_e32 v232, v232
	v_exp_f32_e32 v163, v163
	v_exp_f32_e32 v233, v233
	v_add_f32_e32 v160, 1.0, v160
	v_add_f32_e32 v230, 1.0, v230
	v_add_f32_e32 v161, 1.0, v161
	v_add_f32_e32 v231, 1.0, v231
	v_add_f32_e32 v162, 1.0, v162
	v_add_f32_e32 v232, 1.0, v232
	v_add_f32_e32 v163, 1.0, v163
	v_add_f32_e32 v233, 1.0, v233
	v_rcp_f32_e32 v160, v160
	v_rcp_f32_e32 v230, v230
	v_rcp_f32_e32 v161, v161
	v_rcp_f32_e32 v231, v231
	v_rcp_f32_e32 v162, v162
	v_rcp_f32_e32 v232, v232
	v_rcp_f32_e32 v163, v163
	v_rcp_f32_e32 v233, v233
	v_mul_f32_e32 v20, v20, v160
	v_mul_f32_e32 v21, v21, v230
	v_mul_f32_e32 v22, v22, v161
	v_mul_f32_e32 v23, v23, v231
	v_mul_f32_e32 v16, v16, v162
	v_mul_f32_e32 v17, v17, v232
	v_mul_f32_e32 v18, v18, v163
	v_mul_f32_e32 v19, v19, v233
	v_cvt_pk_bf16_f32 v20, v20, v21
	v_cvt_pk_bf16_f32 v21, v22, v23
	v_cvt_pk_bf16_f32 v22, v16, v17
	v_cvt_pk_bf16_f32 v23, v18, v19
	global_store_dwordx4 v156, v[20:23], s[12:13] offset:256
	s_waitcnt vmcnt(15)
	v_lshlrev_b32_e32 v160, 16, v234
	v_lshlrev_b32_e32 v161, 16, v235
	v_lshlrev_b32_e32 v162, 16, v236
	v_lshlrev_b32_e32 v163, 16, v237
	v_and_b32_e32 v234, 0xffff0000, v234
	v_and_b32_e32 v235, 0xffff0000, v235
	v_and_b32_e32 v236, 0xffff0000, v236
	v_and_b32_e32 v237, 0xffff0000, v237
	v_mul_f32_e32 v160, 0xbfb8aa3b, v160
	v_mul_f32_e32 v234, 0xbfb8aa3b, v234
	v_mul_f32_e32 v161, 0xbfb8aa3b, v161
	v_mul_f32_e32 v235, 0xbfb8aa3b, v235
	v_mul_f32_e32 v162, 0xbfb8aa3b, v162
	v_mul_f32_e32 v236, 0xbfb8aa3b, v236
	v_mul_f32_e32 v163, 0xbfb8aa3b, v163
	v_mul_f32_e32 v237, 0xbfb8aa3b, v237
	v_exp_f32_e32 v160, v160
	v_exp_f32_e32 v234, v234
	v_exp_f32_e32 v161, v161
	v_exp_f32_e32 v235, v235
	v_exp_f32_e32 v162, v162
	v_exp_f32_e32 v236, v236
	v_exp_f32_e32 v163, v163
	v_exp_f32_e32 v237, v237
	v_add_f32_e32 v160, 1.0, v160
	v_add_f32_e32 v234, 1.0, v234
	v_add_f32_e32 v161, 1.0, v161
	v_add_f32_e32 v235, 1.0, v235
	v_add_f32_e32 v162, 1.0, v162
	v_add_f32_e32 v236, 1.0, v236
	v_add_f32_e32 v163, 1.0, v163
	v_add_f32_e32 v237, 1.0, v237
	v_rcp_f32_e32 v160, v160
	v_rcp_f32_e32 v234, v234
	v_rcp_f32_e32 v161, v161
	v_rcp_f32_e32 v235, v235
	v_rcp_f32_e32 v162, v162
	v_rcp_f32_e32 v236, v236
	v_rcp_f32_e32 v163, v163
	v_rcp_f32_e32 v237, v237
	v_mul_f32_e32 v12, v12, v160
	v_mul_f32_e32 v13, v13, v234
	v_mul_f32_e32 v14, v14, v161
	v_mul_f32_e32 v15, v15, v235
	v_mul_f32_e32 v8, v8, v162
	v_mul_f32_e32 v9, v9, v236
	v_mul_f32_e32 v10, v10, v163
	v_mul_f32_e32 v11, v11, v237
	v_cvt_pk_bf16_f32 v12, v12, v13
	v_cvt_pk_bf16_f32 v13, v14, v15
	v_cvt_pk_bf16_f32 v14, v8, v9
	v_cvt_pk_bf16_f32 v15, v10, v11
	global_store_dwordx4 v157, v[12:15], s[12:13]
	s_waitcnt vmcnt(15)
	v_lshlrev_b32_e32 v160, 16, v238
	v_lshlrev_b32_e32 v161, 16, v239
	v_lshlrev_b32_e32 v162, 16, v240
	v_lshlrev_b32_e32 v163, 16, v241
	v_and_b32_e32 v238, 0xffff0000, v238
	v_and_b32_e32 v239, 0xffff0000, v239
	v_and_b32_e32 v240, 0xffff0000, v240
	v_and_b32_e32 v241, 0xffff0000, v241
	v_mul_f32_e32 v160, 0xbfb8aa3b, v160
	v_mul_f32_e32 v238, 0xbfb8aa3b, v238
	v_mul_f32_e32 v161, 0xbfb8aa3b, v161
	v_mul_f32_e32 v239, 0xbfb8aa3b, v239
	v_mul_f32_e32 v162, 0xbfb8aa3b, v162
	v_mul_f32_e32 v240, 0xbfb8aa3b, v240
	v_mul_f32_e32 v163, 0xbfb8aa3b, v163
	v_mul_f32_e32 v241, 0xbfb8aa3b, v241
	v_exp_f32_e32 v160, v160
	v_exp_f32_e32 v238, v238
	v_exp_f32_e32 v161, v161
	v_exp_f32_e32 v239, v239
	v_exp_f32_e32 v162, v162
	v_exp_f32_e32 v240, v240
	v_exp_f32_e32 v163, v163
	v_exp_f32_e32 v241, v241
	v_add_f32_e32 v160, 1.0, v160
	v_add_f32_e32 v238, 1.0, v238
	v_add_f32_e32 v161, 1.0, v161
	v_add_f32_e32 v239, 1.0, v239
	v_add_f32_e32 v162, 1.0, v162
	v_add_f32_e32 v240, 1.0, v240
	v_add_f32_e32 v163, 1.0, v163
	v_add_f32_e32 v241, 1.0, v241
	v_rcp_f32_e32 v160, v160
	v_rcp_f32_e32 v238, v238
	v_rcp_f32_e32 v161, v161
	v_rcp_f32_e32 v239, v239
	v_rcp_f32_e32 v162, v162
	v_rcp_f32_e32 v240, v240
	v_rcp_f32_e32 v163, v163
	v_rcp_f32_e32 v241, v241
	v_mul_f32_e32 v4, v4, v160
	v_mul_f32_e32 v5, v5, v238
	v_mul_f32_e32 v6, v6, v161
	v_mul_f32_e32 v7, v7, v239
	v_mul_f32_e32 v0, v0, v162
	v_mul_f32_e32 v1, v1, v240
	v_mul_f32_e32 v2, v2, v163
	v_mul_f32_e32 v3, v3, v241
	v_cvt_pk_bf16_f32 v4, v4, v5
	v_cvt_pk_bf16_f32 v5, v6, v7
	v_cvt_pk_bf16_f32 v6, v0, v1
	v_cvt_pk_bf16_f32 v7, v2, v3
	global_store_dwordx4 v157, v[4:7], s[12:13] offset:256
	s_cbranch_vccnz .LBB0_671
	s_andn2_b64 vcc, exec, s[6:7]
	s_cbranch_vccnz .LBB0_670
	s_barrier
	s_branch .LBB0_670
